# attention: next item's first K/V tile DMA issued before the current item's epilogue (items start on LDS stage 1)
# speedup vs baseline: 1.0135x; 1.0023x over previous
; __device__ __forceinline__ int ltid() { int t = threadIdx.x; asm volatile("" : "+v"(t)); return t; }
; __device__ __forceinline__ int lsg(int x) { x = __builtin_amdgcn_readfirstlane(x); asm volatile("" : "+s"(x)); return x; }
; __device__ __forceinline__ void phase_attn(KP P, int l_, unsigned char* shm) {
;     const int l = lsg(l_);
;     const int tid = ltid(), wave = tid >> 6, lane = tid & 63, mp = wave >> 2, rq = wave & 3, l15 = lane & 15, g = lane >> 4;
;     const u16* pA = (const u16*)(P->ws + WS_P);
;     u16* OA = (u16*)(P->ws + WS_O);
;     constexpr int KROW = 72, VROW = 136, KT_B = 128 * KROW * 2, VT_B = 128 * VROW * 2, STG = 2 * KT_B + VT_B;
;     const u16* vTg = (const u16*)(P->ws + WS_LO);
;     const float lam_init = 0.8f - 0.6f * __expf(-0.3f * (float)l);
;     float lam;
;     { const float* lq = P->in[11] + (size_t)l * 256; const float s1 = wave_sum(lq[lane] * lq[64 + lane]), s2 = wave_sum(lq[128 + lane] * lq[192 + lane]); lam = __expf(s1) - __expf(s2) + lam_init; }
;     for (int it = blockIdx.x; it < 4096; it += gridDim.x) {
.LBB0_2646:
	s_or_b64 exec, exec, s[4:5]
	v_readlane_b32 s0, v255, 1
	s_mov_b64 s[42:43], s[72:73]
	s_mov_b32 s8, s0
	s_waitcnt lgkmcnt(0)
	v_mov_b32_e32 v0, v228
	s_barrier
	s_load_dwordx2 s[4:5], s[42:43], 0x58
	s_ashr_i32 s9, s8, 31
	s_lshl_b64 s[6:7], s[8:9], 10
	v_and_b32_e32 v2, 63, v0
	v_lshlrev_b32_e32 v1, 2, v2
	s_waitcnt lgkmcnt(0)
	s_add_u32 s6, s4, s6
	s_addc_u32 s7, s5, s7
	global_load_dword v3, v1, s[6:7]
	global_load_dword v4, v1, s[6:7] offset:256
	v_readlane_b32 s0, v254, 6
	v_readlane_b32 s1, v254, 7
	s_and_b64 vcc, exec, s[0:1]
	s_waitcnt vmcnt(0)
	v_mul_f32_e32 v6, v3, v4
	s_nop 1
	v_mov_b32_dpp v6, v6 quad_perm:[1,0,3,2] row_mask:0xf bank_mask:0xf bound_ctrl:1
	v_fmac_f32_e32 v6, v3, v4
	v_mov_b32_e32 v4, v5
	s_nop 0
	v_add_f32_dpp v3, v6, v6 quad_perm:[2,3,0,1] row_mask:0xf bank_mask:0xf bound_ctrl:1
	s_nop 1
	v_add_f32_dpp v3, v3, v3 row_half_mirror row_mask:0xf bank_mask:0xf bound_ctrl:1
	s_nop 1
	v_add_f32_dpp v3, v3, v3 row_mirror row_mask:0xf bank_mask:0xf bound_ctrl:1
	s_nop 1
	v_mov_b32_dpp v4, v3 row_bcast:15 row_mask:0xa bank_mask:0xf
	v_add_f32_e32 v3, v3, v4
	v_mov_b32_e32 v4, v5
	s_nop 1
	v_mov_b32_dpp v4, v3 row_bcast:31 row_mask:0xc bank_mask:0xf
	v_add_f32_e32 v3, v3, v4
	s_nop 0
	v_readlane_b32 s4, v3, 63
	global_load_dword v3, v1, s[6:7] offset:512
	global_load_dword v4, v1, s[6:7] offset:768
	s_waitcnt vmcnt(0)
	v_mul_f32_e32 v6, v3, v4
	s_nop 1
	v_mov_b32_dpp v6, v6 quad_perm:[1,0,3,2] row_mask:0xf bank_mask:0xf bound_ctrl:1
	v_fmac_f32_e32 v6, v3, v4
	v_mov_b32_e32 v4, v5
	s_nop 0
	v_add_f32_dpp v3, v6, v6 quad_perm:[2,3,0,1] row_mask:0xf bank_mask:0xf bound_ctrl:1
	s_nop 1
	v_add_f32_dpp v3, v3, v3 row_half_mirror row_mask:0xf bank_mask:0xf bound_ctrl:1
	s_nop 1
	v_add_f32_dpp v3, v3, v3 row_mirror row_mask:0xf bank_mask:0xf bound_ctrl:1
	s_nop 1
	v_mov_b32_dpp v4, v3 row_bcast:15 row_mask:0xa bank_mask:0xf
	v_add_f32_e32 v3, v3, v4
	v_mov_b32_e32 v4, v5
	s_nop 1
	v_mov_b32_dpp v4, v3 row_bcast:31 row_mask:0xc bank_mask:0xf
	v_add_f32_e32 v3, v3, v4
	s_nop 0
	v_readlane_b32 s5, v3, 63
	s_cbranch_vccz .LBB0_2668
; __device__ __forceinline__ int ltid() { int t = threadIdx.x; asm volatile("" : "+v"(t)); return t; }
; __device__ __forceinline__ void phase_attn(KP P, int l_, unsigned char* shm) {
;     ...
;     const int tid = ltid(), wave = tid >> 6, lane = tid & 63, mp = wave >> 2, rq = wave & 3, l15 = lane & 15, g = lane >> 4;
;     const u16* pA = (const u16*)(P->ws + WS_P);
;     u16* OA = (u16*)(P->ws + WS_O);
;     constexpr int KROW = 72, VROW = 136, KT_B = 128 * KROW * 2, VT_B = 128 * VROW * 2, STG = 2 * KT_B + VT_B;
;     const u16* vTg = (const u16*)(P->ws + WS_LO);
;     const float lam_init = 0.8f - 0.6f * __expf(-0.3f * (float)l);
;     float lam;
;     { const float* lq = P->in[11] + (size_t)l * 256; const float s1 = wave_sum(lq[lane] * lq[64 + lane]), s2 = wave_sum(lq[128 + lane] * lq[192 + lane]); lam = __expf(s1) - __expf(s2) + lam_init; }
;     for (int it = blockIdx.x; it < 4096; it += gridDim.x) {
;         const int j = it & 255, pi = 15 - (it >> 8), bh = j >> 1, half = j & 1, b = bh >> 2, h = bh & 3;
;         const int qb = (pi >> 1) * 4 + ((pi & 1) ? (half ? 2 : 3) : (half ? 1 : 0));
;         const int q0 = qb * 64, nt = (qb >> 1) + 1;
;         const size_t tok0 = (size_t)b * SEQ;
;         bf16x8 qf[2];
;         { const u16* qp = pA + (tok0 + q0 + rq * 16 + l15) * 1536 + h * 128 + mp * 64 + g * 8;
;           qf[0] = *(const bf16x8*)qp; qf[1] = *(const bf16x8*)(qp + 32); }
;         f32x4 ot[8];
; #pragma unroll
;         for (int e = 0; e < 8; ++e) ot[e] = (f32x4){0.f, 0.f, 0.f, 0.f};
;         float mrun = -INFINITY, lrun = 0.f;
;         uint4 kreg0, kreg1, kreg2, kreg3, vreg0, vreg1, vreg2, vreg3;
;         const int kc_key = (tid >> 3) & 63, kc_ch = tid & 7, vc_e = tid >> 4, vc_ch = tid & 15;
;         const u16* kgb = pA + (tok0 + kc_key) * 1536 + 512 + h * 128 + kc_ch * 8;
;         const u16* vTb = vTg + ((size_t)bh * 128 + vc_e) * SEQ + vc_ch * 8;
;     ...
;                         const int qr = rq * 16 + l15;
; #pragma unroll
;                         for (int kt = 0; kt < 4; ++kt)
; #pragma unroll
;                             for (int jj = 0; jj < 4; ++jj) if (kt * 16 + g * 4 + jj > qr) st[kt][jj] = -INFINITY;
	v_cvt_f32_i32_e32 v3, s8
	v_mov_b32_e32 v6, 0x3fb8aa3b
	v_mul_f32_e32 v4, s4, v6
	v_mul_f32_e32 v6, s5, v6
	v_mul_f32_e32 v3, 0xbe99999a, v3
	v_mul_f32_e32 v3, 0x3fb8aa3b, v3
	v_exp_f32_e32 v3, v3
	v_exp_f32_e32 v4, v4
	v_exp_f32_e32 v6, v6
	v_mov_b32_e32 v7, 0x3f4ccccd
	v_fmamk_f32 v3, v3, 0xbf19999a, v7
	v_lshrrev_b32_e32 v8, 4, v2
	v_sub_f32_e32 v4, v4, v6
	v_add_f32_e32 v165, v3, v4
	v_and_b32_e32 v4, 15, v0
	v_bfe_u32 v10, v0, 6, 2
	v_lshlrev_b32_e32 v164, 2, v8
	v_lshl_or_b32 v194, v10, 4, v4
	v_sub_f32_e32 v197, 1.0, v3
	v_or_b32_e32 v3, 2, v164
	v_cmp_gt_u32_e64 s[12:13], v3, v194
	v_or_b32_e32 v3, 3, v164
	v_cmp_gt_u32_e64 s[14:15], v3, v194
	v_or_b32_e32 v3, 16, v164
	v_cmp_gt_u32_e64 s[16:17], v3, v194
	v_or_b32_e32 v3, 17, v164
	v_cmp_gt_u32_e64 s[18:19], v3, v194
	v_or_b32_e32 v3, 18, v164
	s_load_dwordx2 s[48:49], s[42:43], 0xf8
	v_cmp_gt_u32_e64 s[20:21], v3, v194
	v_or_b32_e32 v3, 19, v164
	v_cmp_gt_u32_e64 s[22:23], v3, v194
	v_or_b32_e32 v3, 32, v164
	v_lshlrev_b32_e32 v6, 3, v0
	v_cmp_gt_u32_e64 s[24:25], v3, v194
	v_or_b32_e32 v3, 33, v164
	v_and_b32_e32 v2, 56, v6
	v_and_b32_e32 v6, 0x78, v6
	v_cmp_gt_u32_e64 s[26:27], v3, v194
	v_or_b32_e32 v3, 34, v164
	v_lshlrev_b32_e32 v160, 1, v6
	v_mov_b32_e32 v161, v5
	v_cmp_gt_u32_e64 s[28:29], v3, v194
	v_or_b32_e32 v3, 35, v164
	v_bfe_u32 v169, v0, 3, 6
	s_waitcnt lgkmcnt(0)
	v_lshl_add_u64 v[6:7], s[48:49], 0, v[160:161]
	s_mov_b64 s[0:1], 0x2bb00000
	v_cmp_gt_u32_e64 s[30:31], v3, v194
	v_or_b32_e32 v3, 48, v164
	v_lshl_add_u64 v[162:163], v[6:7], 0, s[0:1]
	v_mul_u32_u24_e32 v6, 0x48, v169
	v_cmp_gt_u32_e64 s[34:35], v3, v194
	v_or_b32_e32 v3, 49, v164
	s_add_u32 s50, s48, 0x17b00000
	v_ashrrev_i32_e32 v158, 4, v0
	v_lshlrev_b32_e32 v161, 1, v6
	v_lshlrev_b32_e32 v6, 1, v2
	s_movk_i32 s0, 0x88
	v_cmp_gt_u32_e64 s[36:37], v3, v194
	v_or_b32_e32 v3, 50, v164
	s_addc_u32 s51, s49, 0
	v_lshrrev_b32_e32 v9, 6, v0
	v_ashrrev_i32_e32 v11, 8, v0
	v_ashrrev_i32_e32 v159, 31, v158
	v_add3_u32 v190, 0, v161, v6
	v_mul_lo_u32 v6, v158, s0
	v_xor_b32_e32 v195, 64, v1
	v_xor_b32_e32 v196, 0x80, v1
	v_lshl_add_u32 v1, v4, 2, 0
	s_movk_i32 s0, 0x100
	v_cmp_gt_u32_e64 s[38:39], v3, v194
	v_or_b32_e32 v3, 51, v164
	s_add_u32 s60, s48, 0x27b00000
	v_lshlrev_b32_e32 v154, 6, v11
	v_lshlrev_b32_e32 v156, 3, v8
	v_lshlrev_b32_e32 v191, 1, v6
	v_cmp_gt_u32_e64 s[6:7], s0, v0
	v_cmp_gt_u32_e64 s[40:41], v3, v194
	v_lshlrev_b32_e32 v3, 8, v8
	v_lshl_add_u32 v6, v10, 13, v1
	v_lshl_add_u32 v1, v9, 13, v1
	v_lshlrev_b64 v[166:167], 12, v[158:159]
	v_and_b32_e32 v0, 7, v0
	s_addc_u32 s61, s49, 0
	v_ashrrev_i32_e32 v155, 31, v154
	v_add3_u32 v192, 0, v191, v160
	v_mul_i32_i24_e32 v193, 0x4800, v11
	v_cmp_eq_u32_e64 s[4:5], 1, v11
	s_lshl_b64 s[54:55], s[8:9], 9
	v_mul_u32_u24_e32 v198, 0x90, v4
	v_mul_u32_u24_e32 v199, 0x110, v4
	v_cmp_gt_u32_e64 s[8:9], v164, v194
	v_cmp_lt_u32_e64 s[10:11], v164, v194
	v_lshl_or_b32 v166, v4, 4, v166
	v_lshlrev_b32_e32 v168, 4, v0
	v_mov_b32_e32 v157, v5
	v_lshlrev_b32_e32 v170, 1, v156
	v_lshlrev_b32_e32 v172, 1, v2
	v_add_u32_e32 v200, v6, v3
	v_add_u32_e32 v201, v1, v3
	v_bfe_u32 v0, v228, 3, 6
	v_bfe_u32 v1, v0, 1, 3
	v_and_b32_e32 v2, 7, v228
	v_xor_b32_e32 v1, v1, v2
	v_lshlrev_b32_e32 v1, 4, v1
	v_lshl_add_u32 v190, v0, 7, v1
	v_lshrrev_b32_e32 v0, 4, v228
	v_and_b32_e32 v1, 15, v0
	v_add_u32_e32 v2, 4, v1
	v_bfe_u32 v2, v2, 3, 1
	v_xor_b32_e32 v1, v1, v2
	v_and_b32_e32 v2, 15, v228
	v_xor_b32_e32 v1, v1, v2
	v_lshlrev_b32_e32 v1, 4, v1
	v_lshl_add_u32 v192, v0, 8, v1
	v_add_u32_e32 v192, 0x8000, v192
	v_and_b32_e32 v0, 15, v228
	v_bfe_u32 v1, v228, 4, 2
	v_lshrrev_b32_e32 v2, 1, v0
	v_xor_b32_e32 v2, v2, v1
	v_lshlrev_b32_e32 v3, 7, v0
	v_lshl_add_u32 v198, v2, 4, v3
	v_xor_b32_e32 v2, 4, v2
	v_lshl_add_u32 v199, v2, 4, v3
	v_lshrrev_b32_e32 v2, 8, v228
	v_lshlrev_b32_e32 v2, 14, v2
	v_add_u32_e32 v198, v198, v2
	v_add_u32_e32 v199, v199, v2
	v_add_u32_e32 v2, 4, v0
	v_bfe_u32 v2, v2, 3, 1
	v_xor_b32_e32 v2, v2, v0
	v_lshlrev_b32_e32 v3, 8, v0
	v_add_u32_e32 v3, 0x8000, v3
	v_xor_b32_e32 v1, v1, v2
	v_lshl_add_u32 v161, v1, 4, v3
	v_xor_b32_e32 v2, 4, v1
	v_lshl_add_u32 v191, v2, 4, v3
	v_xor_b32_e32 v2, 8, v1
	v_lshl_add_u32 v160, v2, 4, v3
	v_xor_b32_e32 v2, 12, v1
	v_lshl_add_u32 v210, v2, 4, v3
	v_lshrrev_b32_e32 v0, 6, v228
	v_and_b32_e32 v1, 63, v228
	s_nop 0
	v_readfirstlane_b32 s32, v0
	s_lshl_b32 s32, s32, 12
	v_and_b32_e32 v2, 3, v0
	v_lshrrev_b32_e32 v3, 3, v1
	v_lshl_add_u32 v2, v2, 5, v3
	v_mul_u32_u24_e32 v2, 0xc00, v2
	v_lshrrev_b32_e32 v6, 2, v0
	v_lshl_add_u32 v2, v6, 7, v2
	v_and_b32_e32 v6, 7, v1
	v_lshrrev_b32_e32 v7, 1, v3
	v_xor_b32_e32 v6, v6, v7
	v_xor_b32_e32 v7, 4, v6
	v_lshl_add_u32 v202, v6, 4, v2
	v_lshl_add_u32 v203, v7, 4, v2
	v_add_u32_e32 v203, 0x6000, v203
	v_lshl_add_u32 v211, v6, 4, v2
	v_add_u32_e32 v211, 0xc000, v211
	v_lshl_add_u32 v235, v7, 4, v2
	v_add_u32_e32 v235, 0x12000, v235
	v_lshrrev_b32_e32 v3, 4, v1
	v_and_b32_e32 v6, 15, v1
	v_lshl_add_u32 v2, v0, 4, v3
	v_lshlrev_b32_e32 v2, 12, v2
	v_mov_b32_e32 v7, v3
	v_add_u32_e32 v8, 4, v7
	v_bfe_u32 v8, v8, 3, 1
	v_xor_b32_e32 v7, v7, v8
	v_xor_b32_e32 v7, v7, v6
	v_lshl_add_u32 v239, v7, 4, v2
	v_add_u32_e32 v7, 4, v3
	v_add_u32_e32 v8, 4, v7
	v_bfe_u32 v8, v8, 3, 1
	v_xor_b32_e32 v7, v7, v8
	v_xor_b32_e32 v7, v7, v6
	v_lshl_add_u32 v240, v7, 4, v2
	v_add_u32_e32 v240, 0x4000, v240
	v_add_u32_e32 v7, 8, v3
	v_add_u32_e32 v8, 4, v7
	v_bfe_u32 v8, v8, 3, 1
	v_xor_b32_e32 v7, v7, v8
	v_xor_b32_e32 v7, v7, v6
	v_lshl_add_u32 v247, v7, 4, v2
	v_add_u32_e32 v247, 0x8000, v247
	v_add_u32_e32 v7, 12, v3
	v_add_u32_e32 v8, 4, v7
	v_bfe_u32 v8, v8, 3, 1
	v_xor_b32_e32 v7, v7, v8
	v_xor_b32_e32 v7, v7, v6
	v_lshl_add_u32 v193, v7, 4, v2
	v_add_u32_e32 v193, 0xc000, v193
	s_mov_b32 s62, s2
	s_mov_b32 s65, 0
	s_branch .LBB0_2649

; __device__ __forceinline__ void phase_attn(KP P, int l_, unsigned char* shm) {
;     ...
;     for (int it = blockIdx.x; it < 4096; it += gridDim.x) {
;         const int j = it & 255, pi = 15 - (it >> 8), bh = j >> 1, half = j & 1, b = bh >> 2, h = bh & 3;
;         const int qb = (pi >> 1) * 4 + ((pi & 1) ? (half ? 2 : 3) : (half ? 1 : 0));
;         const int q0 = qb * 64, nt = (qb >> 1) + 1;
;         const size_t tok0 = (size_t)b * SEQ;
;         bf16x8 qf[2];
;         { const u16* qp = pA + (tok0 + q0 + rq * 16 + l15) * 1536 + h * 128 + mp * 64 + g * 8;
;           qf[0] = *(const bf16x8*)qp; qf[1] = *(const bf16x8*)(qp + 32); }
;         f32x4 ot[8];
; #pragma unroll
;         for (int e = 0; e < 8; ++e) ot[e] = (f32x4){0.f, 0.f, 0.f, 0.f};
;         float mrun = -INFINITY, lrun = 0.f;
;         uint4 kreg0, kreg1, kreg2, kreg3, vreg0, vreg1, vreg2, vreg3;
;         const int kc_key = (tid >> 3) & 63, kc_ch = tid & 7, vc_e = tid >> 4, vc_ch = tid & 15;
;         const u16* kgb = pA + (tok0 + kc_key) * 1536 + 512 + h * 128 + kc_ch * 8;
;         const u16* vTb = vTg + ((size_t)bh * 128 + vc_e) * SEQ + vc_ch * 8;
;     ...
;         ATT_GLOAD(0); ATT_LSTORE(0); __syncthreads();
.LBB0_2649:
	s_lshr_b32 s0, s62, 8
	s_and_b32 s1, s62, 7
	s_lshl_b32 s1, s1, 4
	s_or_b32 s1, s1, s0
	s_bfe_u32 s52, s62, 0x50003
	s_and_b32 s56, s0, 30
	s_add_i32 s52, s52, s56
	s_and_b32 s52, s52, 31
	s_sub_i32 s56, 31, s52
	s_bitcmp1_b32 s0, 0
	s_cselect_b32 s52, s56, s52
	s_lshr_b32 s56, s52, 1
	s_xor_b32 s57, s52, s56
	s_and_b32 s57, s57, 1
	s_sub_i32 s56, 15, s56
	s_lshl_b32 s56, s56, 8
	s_lshl_b32 s1, s1, 1
	s_or_b32 s98, s56, s1
	s_or_b32 s98, s98, s57
	s_bfe_u32 s0, s98, 0x70001
	s_lshl_b32 s52, s0, 19
	v_lshl_add_u64 v[174:175], v[166:167], 0, s[52:53]
	s_ashr_i32 s52, s98, 8
	s_sub_i32 s52, 15, s52
	s_lshl_b32 s1, s98, 7
	s_and_b32 s56, s98, 1
	s_lshl_b32 s57, s52, 1
	s_and_b32 s1, s1, 0x300
	s_and_b32 s57, s57, 0x7ffffffc
	s_and_b32 s52, s52, 1
	s_xor_b32 s58, s56, 3
	s_cmp_eq_u32 s52, 0
	s_cselect_b32 s52, s56, s58
	s_or_b32 s58, s52, s57
	s_lshl_b32 s56, s98, 8
	s_lshl_b32 s52, s58, 6
	s_and_b32 s59, s56, 0xf800
	s_add_i32 s52, s52, s59
	v_or_b32_e32 v4, s52, v194
	s_lshl_b32 s52, s98, 6
	v_mov_b64_e32 v[0:1], s[50:51]
	s_and_b32 s63, s52, 0x180
	v_mad_u64_u32 v[0:1], s[56:57], v4, s83, v[0:1]
	s_lshl_b32 s52, s63, 1
	s_mul_i32 s64, s59, 0xc00
	s_add_i32 s64, s64, s1
	s_add_u32 s98, s50, s64
	s_addc_u32 s99, s51, 0
	s_add_u32 s98, s98, 0x400
	s_addc_u32 s99, s99, 0
	s_lshl_b32 s64, s0, 19
	s_add_u32 s100, s48, s64
	s_addc_u32 s101, s49, 0
	s_add_u32 s100, s100, 0x2bb00000
	s_addc_u32 s101, s101, 0
	s_waitcnt vmcnt(1)
	v_lshl_add_u64 v[18:19], v[0:1], 0, s[52:53]
	v_or_b32_e32 v0, s59, v169
	v_mul_u32_u24_e32 v0, 0x600, v0
	v_lshlrev_b32_e32 v50, 1, v0
	v_mov_b32_e32 v51, v5
	v_lshl_add_u64 v[0:1], s[50:51], 0, v[50:51]
	v_lshl_add_u64 v[0:1], v[0:1], 0, s[52:53]
	v_mov_b32_e32 v173, v5
	s_lshl_b32 s52, s0, 7
	v_lshl_add_u64 v[6:7], v[0:1], 0, v[172:173]
	v_lshl_add_u64 v[0:1], s[52:53], 0, v[158:159]
	s_mov_b32 s0, 0x30000
	v_lshlrev_b64 v[0:1], 12, v[0:1]
	v_add_co_u32_e32 v14, vcc, s0, v6
	v_lshl_add_u64 v[20:21], v[162:163], 0, v[0:1]
	s_nop 0
	v_addc_co_u32_e32 v15, vcc, 0, v7, vcc
	s_mov_b32 s0, 0x20000
	s_waitcnt vmcnt(0)
	v_add_co_u32_e32 v22, vcc, s0, v20
	s_cmp_lg_u32 s65, 0
	s_cbranch_scc1 .Lat_skipdma
	s_add_i32 s1, s32, 0x10000
	s_mov_b32 m0, s1
	s_nop 0
	global_load_lds_dwordx4 v202, s[98:99]
	s_add_i32 m0, s1, 0x400
	s_nop 0
	global_load_lds_dwordx4 v203, s[98:99]
	s_add_i32 m0, s1, 0x800
	s_nop 0
	global_load_lds_dwordx4 v211, s[98:99]
	s_add_i32 m0, s1, 0xc00
	s_nop 0
	global_load_lds_dwordx4 v235, s[98:99]
	s_add_i32 m0, s1, 0x8000
	s_nop 0
	global_load_lds_dwordx4 v239, s[100:101]
	s_add_i32 m0, s1, 0x8400
	s_nop 0
	global_load_lds_dwordx4 v240, s[100:101]
	s_add_i32 m0, s1, 0x8800
	s_nop 0
	global_load_lds_dwordx4 v247, s[100:101]
	s_add_i32 m0, s1, 0x8c00
	s_nop 0
	global_load_lds_dwordx4 v193, s[100:101]
.Lat_skipdma:
	s_nop 0
	s_nop 0
	v_addc_co_u32_e32 v23, vcc, 0, v21, vcc
	s_nop 0
	v_add_co_u32_e32 v22, vcc, s85, v20
	s_mov_b32 s0, 0x60000
	s_nop 0
	v_addc_co_u32_e32 v23, vcc, 0, v21, vcc
	v_add_co_u32_e32 v20, vcc, s0, v20
	v_lshl_add_u64 v[18:19], v[154:155], 1, v[18:19]
	v_mov_b32_e32 v171, v5
	v_addc_co_u32_e32 v21, vcc, 0, v21, vcc
	v_lshl_add_u64 v[22:23], v[18:19], 0, v[170:171]
	global_load_dwordx4 v[18:21], v[22:23], off
	s_nop 0
	global_load_dwordx4 v[22:25], v[22:23], off offset:64
	v_mov_b32_e32 v70, v5
	v_mov_b32_e32 v71, v5
	v_mov_b32_e32 v72, v5
	v_mov_b32_e32 v73, v5
	v_mov_b64_e32 v[66:67], v[70:71]
	v_mov_b64_e32 v[62:63], v[70:71]
	v_mov_b64_e32 v[54:55], v[70:71]
	v_mov_b64_e32 v[46:47], v[70:71]
	v_mov_b64_e32 v[42:43], v[70:71]
	s_and_b32 s65, s58, 0x7ffffffe
	v_or3_b32 v176, v168, s1, v50
	v_mov_b64_e32 v[50:51], v[70:71]
	v_mov_b64_e32 v[58:59], v[70:71]
	s_mov_b32 s52, 0
	v_mov_b32_e32 v177, v157
	v_mov_b32_e32 v171, 0
	v_mov_b32_e32 v248, 0
	v_mov_b32_e32 v249, 0
	v_mov_b32_e32 v250, 0
	v_mov_b32_e32 v251, 0
	v_mov_b32_e32 v252, 0xff800000
	v_mov_b32_e32 v253, 0xff800000
	v_mov_b64_e32 v[68:69], v[72:73]
	v_mov_b64_e32 v[64:65], v[72:73]
	v_mov_b64_e32 v[56:57], v[72:73]
	v_mov_b64_e32 v[48:49], v[72:73]
	v_mov_b64_e32 v[44:45], v[72:73]
	s_lshr_b32 s59, s58, 1
	s_add_i32 s64, s58, -1
	s_add_i32 s65, s65, 2
	v_mov_b64_e32 v[52:53], v[72:73]
	v_mov_b64_e32 v[60:61], v[72:73]
	s_mov_b32 s70, 0
	s_waitcnt vmcnt(0) lgkmcnt(0)
	s_barrier
	s_branch .LBB0_2651

; __device__ __forceinline__ void phase_attn(KP P, int l_, unsigned char* shm) {
;     ...
;         for (int t = 0; t < nt; ++t) {
;             if (t + 1 < nt) ATT_GLOAD(t + 1);
;             const unsigned char* base = shm + (t & 1) * STG;
; #pragma unroll
;             for (int hf = 0; hf < 2; ++hf) {
;                 const int kb = 2 * t + hf;
;                 if (kb <= qb) {
;                     const u16* Ks = (const u16*)(base + mp * KT_B) + hf * 64 * KROW;
;                     const u16* Vt = (const u16*)(base + 2 * KT_B) + hf * 64;
.LBB0_2651:
	s_cmp_lt_u32 s70, s59
	s_cselect_b64 s[56:57], -1, 0
	s_cmp_ge_u32 s70, s59
	s_cbranch_scc1 .LBB0_2653
	s_add_u32 s98, s98, 0x60000
	s_addc_u32 s99, s99, 0
	s_add_u32 s100, s100, 0x100
	s_addc_u32 s101, s101, 0
	s_bitcmp0_b32 s70, 0
	s_cselect_b32 s1, 0, 0x10000
	s_add_i32 s1, s1, s32
	s_mov_b32 m0, s1
	s_nop 0
	global_load_lds_dwordx4 v202, s[98:99]
	s_add_i32 m0, s1, 0x400
	s_nop 0
	global_load_lds_dwordx4 v203, s[98:99]
	s_add_i32 m0, s1, 0x800
	s_nop 0
	global_load_lds_dwordx4 v211, s[98:99]
	s_add_i32 m0, s1, 0xc00
	s_nop 0
	global_load_lds_dwordx4 v235, s[98:99]
	s_add_i32 m0, s1, 0x8000
	s_nop 0
	global_load_lds_dwordx4 v239, s[100:101]
	s_add_i32 m0, s1, 0x8400
	s_nop 0
	global_load_lds_dwordx4 v240, s[100:101]
	s_add_i32 m0, s1, 0x8800
	s_nop 0
	global_load_lds_dwordx4 v247, s[100:101]
	s_add_i32 m0, s1, 0x8c00
	s_nop 0
	global_load_lds_dwordx4 v193, s[100:101]
.LBB0_2653:
	s_bitcmp1_b32 s70, 0
	s_cselect_b32 s0, 0, 0x10000
	v_add_u32_e32 v208, s0, v198
	v_add_u32_e32 v209, s0, v199
	s_cmp_gt_u32 s52, s58
	v_add_u32_e32 v207, s0, v161
	v_add_u32_e32 v206, s0, v191
	v_add_u32_e32 v205, s0, v160
	v_add_u32_e32 v204, s0, v210
	s_cbranch_scc0 .LBB0_2656
	s_cmp_ge_u32 s52, s58
	s_cbranch_scc0 .LBB0_2659

; __device__ __forceinline__ float shfl_xor_l(float v, int m, int lane) { return __int_as_float(__builtin_amdgcn_ds_bpermute((lane ^ m) << 2, __float_as_int(v))); }
; __device__ __forceinline__ void phase_attn(KP P, int l_, unsigned char* shm) {
;     ...
;         lrun += shfl_xor_l(lrun, 16, lane); lrun += shfl_xor_l(lrun, 32, lane);
;         const float inv = __builtin_amdgcn_rcpf(lrun);
;         float* X = (float*)shm;
;         if (mp == 1) {
; #pragma unroll
;             for (int e = 0; e < 8; ++e)
; #pragma unroll
;                 for (int jj = 0; jj < 4; ++jj) X[(rq * 128 + e * 16 + g * 4 + jj) * 16 + l15] = ot[e][jj] * inv * lam;
;         }
.LBB0_2663:
	s_waitcnt vmcnt(7)
	s_add_i32 s0, s62, s44
	s_mov_b32 s65, 0
	s_cmpk_gt_i32 s0, 0xfff
	s_cbranch_scc1 .Lat_nopref
	s_lshr_b32 s1, s0, 8
	s_and_b32 s0, s0, 7
	s_lshl_b32 s0, s0, 4
	s_or_b32 s0, s0, s1
	s_lshr_b32 s1, s0, 2
	s_mul_i32 s1, s1, 0x600000
	s_and_b32 s64, s0, 3
	s_lshl_b32 s64, s64, 8
	s_add_i32 s1, s1, s64
	s_add_u32 s98, s50, s1
	s_addc_u32 s99, s51, 0
	s_add_u32 s98, s98, 0x400
	s_addc_u32 s99, s99, 0
	s_lshl_b32 s0, s0, 19
	s_add_u32 s100, s48, s0
	s_addc_u32 s101, s49, 0
	s_add_u32 s100, s100, 0x2bb00000
	s_addc_u32 s101, s101, 0
	s_mov_b32 s65, 1
	s_add_i32 s1, s32, 0x10000
	s_mov_b32 m0, s1
	s_nop 0
	global_load_lds_dwordx4 v202, s[98:99]
	s_add_i32 m0, s1, 0x400
	s_nop 0
	global_load_lds_dwordx4 v203, s[98:99]
	s_add_i32 m0, s1, 0x800
	s_nop 0
	global_load_lds_dwordx4 v211, s[98:99]
	s_add_i32 m0, s1, 0xc00
	s_nop 0
	global_load_lds_dwordx4 v235, s[98:99]
	s_add_i32 m0, s1, 0x8000
	s_nop 0
	global_load_lds_dwordx4 v239, s[100:101]
	s_add_i32 m0, s1, 0x8400
	s_nop 0
	global_load_lds_dwordx4 v240, s[100:101]
	s_add_i32 m0, s1, 0x8800
	s_nop 0
	global_load_lds_dwordx4 v247, s[100:101]
	s_add_i32 m0, s1, 0x8c00
	s_nop 0
	global_load_lds_dwordx4 v193, s[100:101]
.Lat_nopref:
	ds_bpermute_b32 v0, v195, v171
	s_waitcnt lgkmcnt(0)
	v_add_f32_e32 v0, v171, v0
	ds_bpermute_b32 v1, v196, v0
	s_waitcnt lgkmcnt(0)
	v_add_f32_e32 v0, v0, v1
	v_rcp_f32_e32 v0, v0
	s_and_saveexec_b64 s[56:57], s[4:5]
	s_cbranch_execz .LBB0_2665
	v_mul_f32_e32 v1, v58, v0
	v_mul_f32_e32 v2, v59, v0
	v_mul_f32_e32 v1, v165, v1
	v_mul_f32_e32 v2, v165, v2
	ds_write2_b32 v200, v1, v2 offset1:16
	v_mul_f32_e32 v1, v60, v0
	v_mul_f32_e32 v2, v61, v0
	v_mul_f32_e32 v1, v165, v1
	v_mul_f32_e32 v2, v165, v2
	ds_write2_b32 v200, v1, v2 offset0:32 offset1:48
	v_mul_f32_e32 v1, v50, v0
	v_mul_f32_e32 v2, v51, v0
	v_mul_f32_e32 v1, v165, v1
	v_mul_f32_e32 v2, v165, v2
	v_add_u32_e32 v3, 0x400, v200
	ds_write2_b32 v3, v1, v2 offset1:16
	v_mul_f32_e32 v1, v52, v0
	v_mul_f32_e32 v2, v53, v0
	v_mul_f32_e32 v1, v165, v1
	v_mul_f32_e32 v2, v165, v2
	ds_write2_b32 v3, v1, v2 offset0:32 offset1:48
	v_mul_f32_e32 v1, v42, v0
	v_mul_f32_e32 v2, v43, v0
	v_mul_f32_e32 v1, v165, v1
	v_mul_f32_e32 v2, v165, v2
	v_add_u32_e32 v3, 0x800, v200
	ds_write2_b32 v3, v1, v2 offset1:16
	v_mul_f32_e32 v1, v44, v0
	v_mul_f32_e32 v2, v45, v0
	v_mul_f32_e32 v1, v165, v1
	v_mul_f32_e32 v2, v165, v2
	ds_write2_b32 v3, v1, v2 offset0:32 offset1:48
	v_mul_f32_e32 v1, v46, v0
	v_mul_f32_e32 v2, v47, v0
	v_mul_f32_e32 v1, v165, v1
	v_mul_f32_e32 v2, v165, v2
	v_add_u32_e32 v3, 0xc00, v200
	ds_write2_b32 v3, v1, v2 offset1:16
	v_mul_f32_e32 v1, v48, v0
	v_mul_f32_e32 v2, v49, v0
	v_mul_f32_e32 v1, v165, v1
	v_mul_f32_e32 v2, v165, v2
	ds_write2_b32 v3, v1, v2 offset0:32 offset1:48
	v_mul_f32_e32 v1, v54, v0
	v_mul_f32_e32 v2, v55, v0
	v_mul_f32_e32 v1, v165, v1
	v_mul_f32_e32 v2, v165, v2
	v_add_u32_e32 v3, 0x1000, v200
	ds_write2_b32 v3, v1, v2 offset1:16
	v_mul_f32_e32 v1, v56, v0
	v_mul_f32_e32 v2, v57, v0
	v_mul_f32_e32 v1, v165, v1
	v_mul_f32_e32 v2, v165, v2
	ds_write2_b32 v3, v1, v2 offset0:32 offset1:48
	v_mul_f32_e32 v1, v62, v0
	v_mul_f32_e32 v2, v63, v0
	v_mul_f32_e32 v1, v165, v1
	v_mul_f32_e32 v2, v165, v2
	v_add_u32_e32 v3, 0x1400, v200
	ds_write2_b32 v3, v1, v2 offset1:16
	v_mul_f32_e32 v1, v64, v0
	v_mul_f32_e32 v2, v65, v0
	v_mul_f32_e32 v1, v165, v1
	v_mul_f32_e32 v2, v165, v2
	ds_write2_b32 v3, v1, v2 offset0:32 offset1:48
	v_mul_f32_e32 v1, v66, v0
	v_mul_f32_e32 v2, v67, v0
	v_mul_f32_e32 v1, v165, v1
	v_mul_f32_e32 v2, v165, v2
	v_add_u32_e32 v3, 0x1800, v200
	ds_write2_b32 v3, v1, v2 offset1:16
	v_mul_f32_e32 v1, v68, v0
	v_mul_f32_e32 v2, v69, v0
	v_mul_f32_e32 v1, v165, v1
	v_mul_f32_e32 v2, v165, v2
	ds_write2_b32 v3, v1, v2 offset0:32 offset1:48
	v_mul_f32_e32 v1, v70, v0
	v_mul_f32_e32 v2, v71, v0
	v_mul_f32_e32 v1, v165, v1
	v_mul_f32_e32 v2, v165, v2
	v_add_u32_e32 v3, 0x1c00, v200
	ds_write2_b32 v3, v1, v2 offset1:16
	v_mul_f32_e32 v1, v72, v0
	v_mul_f32_e32 v2, v73, v0
	v_mul_f32_e32 v1, v165, v1
	v_mul_f32_e32 v2, v165, v2
	ds_write2_b32 v3, v1, v2 offset0:32 offset1:48
